# GEMM K-loops: removed the duplicate post-barrier s_waitcnt lgkmcnt(0) in each MFMA block; added the compute-dtype comment line
# speedup vs baseline: 1.0145x; 1.0003x over previous
.LBB0_135:
	s_add_u32 s6, s52, 0xfffc0080
	s_addc_u32 s7, s53, -1
	s_add_i32 s24, 0, 0x10000
	s_cmp_eq_u32 s72, 12
	s_cselect_b32 s57, s47, s7
	s_cselect_b32 s56, s68, s6
	v_add_u32_e32 v148, s24, v151
	s_cselect_b32 s55, s45, s71
	s_cselect_b32 s54, s69, s70
	s_add_i32 s25, 0, 0x14000
	ds_read_b128 v[140:143], v148
	ds_read_b128 v[144:147], v148 offset:1024
	ds_read_b128 v[156:159], v148 offset:2048
	ds_read_b128 v[160:163], v148 offset:3072
	v_add_u32_e32 v148, s25, v151
	ds_read_b128 v[164:167], v148
	ds_read_b128 v[168:171], v148 offset:1024
	ds_read_b128 v[172:175], v148 offset:2048
	ds_read_b128 v[176:179], v148 offset:3072
	v_lshl_add_u64 v[148:149], s[52:53], 0, v[136:137]
	s_add_i32 m0, s61, 0xc000
	ds_read_b128 v[180:183], v154
	ds_read_b128 v[184:187], v154 offset:1024
	ds_read_b128 v[188:191], v154 offset:2048
	ds_read_b128 v[192:195], v154 offset:3072
	ds_read_b128 v[196:199], v154 offset:4096
	ds_read_b128 v[200:203], v154 offset:5120
	ds_read_b128 v[204:207], v154 offset:6144
	ds_read_b128 v[208:211], v154 offset:7168
	global_load_lds_dwordx4 v[148:149], off
	v_lshl_add_u64 v[148:149], s[52:53], 0, v[138:139]
	s_add_i32 m0, s61, 0xe000
	s_nop 0
	global_load_lds_dwordx4 v[148:149], off
	s_waitcnt vmcnt(8)
	s_waitcnt lgkmcnt(0)
	s_barrier
	s_setprio 1
	v_mfma_f32_16x16x32_bf16 v[126:129], v[140:143], v[180:183], v[126:129]
	v_mfma_f32_16x16x32_bf16 v[122:125], v[156:159], v[180:183], v[122:125]
	v_mfma_f32_16x16x32_bf16 v[110:113], v[140:143], v[188:191], v[110:113]
	v_mfma_f32_16x16x32_bf16 v[106:109], v[156:159], v[188:191], v[106:109]
	v_mfma_f32_16x16x32_bf16 v[94:97], v[140:143], v[196:199], v[94:97]
	v_mfma_f32_16x16x32_bf16 v[90:93], v[156:159], v[196:199], v[90:93]
	v_mfma_f32_16x16x32_bf16 v[78:81], v[140:143], v[204:207], v[78:81]
	v_mfma_f32_16x16x32_bf16 v[74:77], v[156:159], v[204:207], v[74:77]
	v_mfma_f32_16x16x32_bf16 v[126:129], v[144:147], v[184:187], v[126:129]
	v_mfma_f32_16x16x32_bf16 v[122:125], v[160:163], v[184:187], v[122:125]
	v_mfma_f32_16x16x32_bf16 v[110:113], v[144:147], v[192:195], v[110:113]
	v_mfma_f32_16x16x32_bf16 v[106:109], v[160:163], v[192:195], v[106:109]
	v_mfma_f32_16x16x32_bf16 v[94:97], v[144:147], v[200:203], v[94:97]
	v_mfma_f32_16x16x32_bf16 v[90:93], v[160:163], v[200:203], v[90:93]
	v_mfma_f32_16x16x32_bf16 v[78:81], v[144:147], v[208:211], v[78:81]
	v_mfma_f32_16x16x32_bf16 v[74:77], v[160:163], v[208:211], v[74:77]
	v_mfma_f32_16x16x32_bf16 v[118:121], v[164:167], v[180:183], v[118:121]
	v_mfma_f32_16x16x32_bf16 v[114:117], v[172:175], v[180:183], v[114:117]
	v_mfma_f32_16x16x32_bf16 v[102:105], v[164:167], v[188:191], v[102:105]
	v_mfma_f32_16x16x32_bf16 v[98:101], v[172:175], v[188:191], v[98:101]
	v_mfma_f32_16x16x32_bf16 v[86:89], v[164:167], v[196:199], v[86:89]
	v_mfma_f32_16x16x32_bf16 v[82:85], v[172:175], v[196:199], v[82:85]
	v_mfma_f32_16x16x32_bf16 v[70:73], v[164:167], v[204:207], v[70:73]
	v_mfma_f32_16x16x32_bf16 v[66:69], v[172:175], v[204:207], v[66:69]
	v_mfma_f32_16x16x32_bf16 v[118:121], v[168:171], v[184:187], v[118:121]
	v_mfma_f32_16x16x32_bf16 v[114:117], v[176:179], v[184:187], v[114:117]
	v_mfma_f32_16x16x32_bf16 v[102:105], v[168:171], v[192:195], v[102:105]
	v_mfma_f32_16x16x32_bf16 v[98:101], v[176:179], v[192:195], v[98:101]
	v_mfma_f32_16x16x32_bf16 v[86:89], v[168:171], v[200:203], v[86:89]
	v_mfma_f32_16x16x32_bf16 v[82:85], v[176:179], v[200:203], v[82:85]
	v_mfma_f32_16x16x32_bf16 v[70:73], v[168:171], v[208:211], v[70:73]
	v_mfma_f32_16x16x32_bf16 v[66:69], v[176:179], v[208:211], v[66:69]
	s_setprio 0
	s_barrier
	s_add_i32 s6, s24, s60
	v_lshl_add_u64 v[148:149], s[54:55], 0, v[0:1]
	s_mov_b32 m0, s6
	ds_read_b128 v[180:183], v154 offset:16384
	ds_read_b128 v[184:187], v154 offset:17408
	ds_read_b128 v[188:191], v154 offset:18432
	ds_read_b128 v[192:195], v154 offset:19456
	ds_read_b128 v[196:199], v154 offset:20480
	ds_read_b128 v[200:203], v154 offset:21504
	ds_read_b128 v[204:207], v154 offset:22528
	ds_read_b128 v[208:211], v154 offset:23552
	global_load_lds_dwordx4 v[148:149], off
	s_add_i32 m0, s6, 0x2000
	s_add_u32 s6, s54, 0x40000
	v_lshl_add_u64 v[212:213], s[54:55], 0, v[130:131]
	s_addc_u32 s7, s55, 0
	s_add_i32 s24, s25, s60
	global_load_lds_dwordx4 v[212:213], off
	v_lshl_add_u64 v[214:215], s[6:7], 0, v[0:1]
	s_mov_b32 m0, s24
	v_lshl_add_u64 v[216:217], s[56:57], 0, v[132:133]
	global_load_lds_dwordx4 v[214:215], off
	v_lshl_add_u64 v[214:215], s[6:7], 0, v[130:131]
	s_add_i32 m0, s24, 0x2000
	s_nop 0
	global_load_lds_dwordx4 v[214:215], off
	v_lshl_add_u64 v[214:215], s[56:57], 0, v[134:135]
	s_mov_b32 m0, s61
	s_nop 0
	global_load_lds_dwordx4 v[214:215], off
	s_mov_b32 m0, s62
	s_nop 0
	global_load_lds_dwordx4 v[216:217], off
	s_waitcnt vmcnt(8)
	s_waitcnt lgkmcnt(0)
	s_barrier
	s_setprio 1
	v_mfma_f32_16x16x32_bf16 v[62:65], v[140:143], v[180:183], v[62:65]
	v_mfma_f32_16x16x32_bf16 v[58:61], v[156:159], v[180:183], v[58:61]
	v_mfma_f32_16x16x32_bf16 v[46:49], v[140:143], v[188:191], v[46:49]
	v_mfma_f32_16x16x32_bf16 v[42:45], v[156:159], v[188:191], v[42:45]
	v_mfma_f32_16x16x32_bf16 v[30:33], v[140:143], v[196:199], v[30:33]
	v_mfma_f32_16x16x32_bf16 v[26:29], v[156:159], v[196:199], v[26:29]
	v_mfma_f32_16x16x32_bf16 v[14:17], v[140:143], v[204:207], v[14:17]
	v_mfma_f32_16x16x32_bf16 v[10:13], v[156:159], v[204:207], v[10:13]
	v_mfma_f32_16x16x32_bf16 v[62:65], v[144:147], v[184:187], v[62:65]
	v_mfma_f32_16x16x32_bf16 v[58:61], v[160:163], v[184:187], v[58:61]
	v_mfma_f32_16x16x32_bf16 v[46:49], v[144:147], v[192:195], v[46:49]
	v_mfma_f32_16x16x32_bf16 v[42:45], v[160:163], v[192:195], v[42:45]
	v_mfma_f32_16x16x32_bf16 v[30:33], v[144:147], v[200:203], v[30:33]
	v_mfma_f32_16x16x32_bf16 v[26:29], v[160:163], v[200:203], v[26:29]
	v_mfma_f32_16x16x32_bf16 v[14:17], v[144:147], v[208:211], v[14:17]
	v_mfma_f32_16x16x32_bf16 v[10:13], v[160:163], v[208:211], v[10:13]
	v_mfma_f32_16x16x32_bf16 v[54:57], v[164:167], v[180:183], v[54:57]
	v_mfma_f32_16x16x32_bf16 v[50:53], v[172:175], v[180:183], v[50:53]
	v_mfma_f32_16x16x32_bf16 v[38:41], v[164:167], v[188:191], v[38:41]
	v_mfma_f32_16x16x32_bf16 v[34:37], v[172:175], v[188:191], v[34:37]
	v_mfma_f32_16x16x32_bf16 v[22:25], v[164:167], v[196:199], v[22:25]
	v_mfma_f32_16x16x32_bf16 v[18:21], v[172:175], v[196:199], v[18:21]
	v_mfma_f32_16x16x32_bf16 v[6:9], v[164:167], v[204:207], v[6:9]
	v_mfma_f32_16x16x32_bf16 v[2:5], v[172:175], v[204:207], v[2:5]
	v_mfma_f32_16x16x32_bf16 v[54:57], v[168:171], v[184:187], v[54:57]
	v_mfma_f32_16x16x32_bf16 v[50:53], v[176:179], v[184:187], v[50:53]
	v_mfma_f32_16x16x32_bf16 v[38:41], v[168:171], v[192:195], v[38:41]
	v_mfma_f32_16x16x32_bf16 v[34:37], v[176:179], v[192:195], v[34:37]
	v_mfma_f32_16x16x32_bf16 v[22:25], v[168:171], v[200:203], v[22:25]
	v_mfma_f32_16x16x32_bf16 v[18:21], v[176:179], v[200:203], v[18:21]
	v_mfma_f32_16x16x32_bf16 v[6:9], v[168:171], v[208:211], v[6:9]
	v_mfma_f32_16x16x32_bf16 v[2:5], v[176:179], v[208:211], v[2:5]
	s_setprio 0
	s_barrier
	s_add_i32 s24, 0, 0x18000
	v_add_u32_e32 v155, s24, v151
	s_add_i32 s25, 0, 0x1c000
	ds_read_b128 v[140:143], v155
	ds_read_b128 v[144:147], v155 offset:1024
	ds_read_b128 v[156:159], v155 offset:2048
	ds_read_b128 v[160:163], v155 offset:3072
	v_add_u32_e32 v155, s25, v151
	ds_read_b128 v[164:167], v155
	ds_read_b128 v[168:171], v155 offset:1024
	ds_read_b128 v[172:175], v155 offset:2048
	ds_read_b128 v[176:179], v155 offset:3072
	s_add_u32 s6, s56, 0x40000
	s_addc_u32 s7, s57, 0
	s_mov_b32 m0, s63
	v_lshl_add_u64 v[218:219], s[6:7], 0, v[134:135]
	ds_read_b128 v[180:183], v154 offset:32768
	ds_read_b128 v[184:187], v154 offset:33792
	ds_read_b128 v[188:191], v154 offset:34816
	ds_read_b128 v[192:195], v154 offset:35840
	ds_read_b128 v[196:199], v154 offset:36864
	ds_read_b128 v[200:203], v154 offset:37888
	ds_read_b128 v[204:207], v154 offset:38912
	ds_read_b128 v[208:211], v154 offset:39936
	global_load_lds_dwordx4 v[218:219], off
	v_lshl_add_u64 v[218:219], s[6:7], 0, v[132:133]
	s_mov_b32 m0, s64
	s_nop 0
	global_load_lds_dwordx4 v[218:219], off
	s_waitcnt vmcnt(8)
	s_waitcnt lgkmcnt(0)
	s_barrier
	s_setprio 1
	v_mfma_f32_16x16x32_bf16 v[126:129], v[140:143], v[180:183], v[126:129]
	v_mfma_f32_16x16x32_bf16 v[122:125], v[156:159], v[180:183], v[122:125]
	v_mfma_f32_16x16x32_bf16 v[110:113], v[140:143], v[188:191], v[110:113]
	v_mfma_f32_16x16x32_bf16 v[106:109], v[156:159], v[188:191], v[106:109]
	v_mfma_f32_16x16x32_bf16 v[94:97], v[140:143], v[196:199], v[94:97]
	v_mfma_f32_16x16x32_bf16 v[90:93], v[156:159], v[196:199], v[90:93]
	v_mfma_f32_16x16x32_bf16 v[78:81], v[140:143], v[204:207], v[78:81]
	v_mfma_f32_16x16x32_bf16 v[74:77], v[156:159], v[204:207], v[74:77]
	v_mfma_f32_16x16x32_bf16 v[126:129], v[144:147], v[184:187], v[126:129]
	v_mfma_f32_16x16x32_bf16 v[122:125], v[160:163], v[184:187], v[122:125]
	v_mfma_f32_16x16x32_bf16 v[110:113], v[144:147], v[192:195], v[110:113]
	v_mfma_f32_16x16x32_bf16 v[106:109], v[160:163], v[192:195], v[106:109]
	v_mfma_f32_16x16x32_bf16 v[94:97], v[144:147], v[200:203], v[94:97]
	v_mfma_f32_16x16x32_bf16 v[90:93], v[160:163], v[200:203], v[90:93]
	v_mfma_f32_16x16x32_bf16 v[78:81], v[144:147], v[208:211], v[78:81]
	v_mfma_f32_16x16x32_bf16 v[74:77], v[160:163], v[208:211], v[74:77]
	v_mfma_f32_16x16x32_bf16 v[118:121], v[164:167], v[180:183], v[118:121]
	v_mfma_f32_16x16x32_bf16 v[114:117], v[172:175], v[180:183], v[114:117]
	v_mfma_f32_16x16x32_bf16 v[102:105], v[164:167], v[188:191], v[102:105]
	v_mfma_f32_16x16x32_bf16 v[98:101], v[172:175], v[188:191], v[98:101]
	v_mfma_f32_16x16x32_bf16 v[86:89], v[164:167], v[196:199], v[86:89]
	v_mfma_f32_16x16x32_bf16 v[82:85], v[172:175], v[196:199], v[82:85]
	v_mfma_f32_16x16x32_bf16 v[70:73], v[164:167], v[204:207], v[70:73]
	v_mfma_f32_16x16x32_bf16 v[66:69], v[172:175], v[204:207], v[66:69]
	v_mfma_f32_16x16x32_bf16 v[118:121], v[168:171], v[184:187], v[118:121]
	v_mfma_f32_16x16x32_bf16 v[114:117], v[176:179], v[184:187], v[114:117]
	v_mfma_f32_16x16x32_bf16 v[102:105], v[168:171], v[192:195], v[102:105]
	v_mfma_f32_16x16x32_bf16 v[98:101], v[176:179], v[192:195], v[98:101]
	v_mfma_f32_16x16x32_bf16 v[86:89], v[168:171], v[200:203], v[86:89]
	v_mfma_f32_16x16x32_bf16 v[82:85], v[176:179], v[200:203], v[82:85]
	v_mfma_f32_16x16x32_bf16 v[70:73], v[168:171], v[208:211], v[70:73]
	v_mfma_f32_16x16x32_bf16 v[66:69], v[176:179], v[208:211], v[66:69]
	s_setprio 0
	s_barrier
	s_add_i32 s6, s24, s60
	v_lshl_add_u64 v[148:149], v[148:149], 0, s[84:85]
	s_mov_b32 m0, s6
	ds_read_b128 v[180:183], v154 offset:49152
	ds_read_b128 v[184:187], v154 offset:50176
	ds_read_b128 v[188:191], v154 offset:51200
	ds_read_b128 v[192:195], v154 offset:52224
	ds_read_b128 v[196:199], v154 offset:53248
	ds_read_b128 v[200:203], v154 offset:54272
	ds_read_b128 v[204:207], v154 offset:55296
	ds_read_b128 v[208:211], v154 offset:56320
	global_load_lds_dwordx4 v[148:149], off
	s_add_i32 m0, s6, 0x2000
	s_add_u32 s6, s54, 0x40080
	v_lshl_add_u64 v[148:149], v[212:213], 0, s[84:85]
	s_addc_u32 s7, s55, 0
	s_add_i32 s24, s25, s60
	global_load_lds_dwordx4 v[148:149], off
	v_lshl_add_u64 v[148:149], s[6:7], 0, v[0:1]
	s_mov_b32 m0, s24
	s_nop 0
	global_load_lds_dwordx4 v[148:149], off
	v_lshl_add_u64 v[148:149], s[6:7], 0, v[130:131]
	s_add_i32 m0, s24, 0x2000
	s_nop 0
	global_load_lds_dwordx4 v[148:149], off
	v_lshl_add_u64 v[148:149], v[214:215], 0, s[84:85]
	s_mov_b32 m0, s65
	s_nop 0
	global_load_lds_dwordx4 v[148:149], off
	v_lshl_add_u64 v[148:149], v[216:217], 0, s[84:85]
	s_mov_b32 m0, s66
	s_nop 0
	global_load_lds_dwordx4 v[148:149], off
	s_waitcnt vmcnt(8)
	s_waitcnt lgkmcnt(0)
	s_barrier
	s_setprio 1
	v_mfma_f32_16x16x32_bf16 v[62:65], v[140:143], v[180:183], v[62:65]
	v_mfma_f32_16x16x32_bf16 v[58:61], v[156:159], v[180:183], v[58:61]
	v_mfma_f32_16x16x32_bf16 v[46:49], v[140:143], v[188:191], v[46:49]
	v_mfma_f32_16x16x32_bf16 v[42:45], v[156:159], v[188:191], v[42:45]
	v_mfma_f32_16x16x32_bf16 v[30:33], v[140:143], v[196:199], v[30:33]
	v_mfma_f32_16x16x32_bf16 v[26:29], v[156:159], v[196:199], v[26:29]
	v_mfma_f32_16x16x32_bf16 v[14:17], v[140:143], v[204:207], v[14:17]
	v_mfma_f32_16x16x32_bf16 v[10:13], v[156:159], v[204:207], v[10:13]
	v_mfma_f32_16x16x32_bf16 v[62:65], v[144:147], v[184:187], v[62:65]
	v_mfma_f32_16x16x32_bf16 v[58:61], v[160:163], v[184:187], v[58:61]
	v_mfma_f32_16x16x32_bf16 v[46:49], v[144:147], v[192:195], v[46:49]
	v_mfma_f32_16x16x32_bf16 v[42:45], v[160:163], v[192:195], v[42:45]
	v_mfma_f32_16x16x32_bf16 v[30:33], v[144:147], v[200:203], v[30:33]
	v_mfma_f32_16x16x32_bf16 v[26:29], v[160:163], v[200:203], v[26:29]
	v_mfma_f32_16x16x32_bf16 v[14:17], v[144:147], v[208:211], v[14:17]
	v_mfma_f32_16x16x32_bf16 v[10:13], v[160:163], v[208:211], v[10:13]
	v_mfma_f32_16x16x32_bf16 v[54:57], v[164:167], v[180:183], v[54:57]
	v_mfma_f32_16x16x32_bf16 v[50:53], v[172:175], v[180:183], v[50:53]
	v_mfma_f32_16x16x32_bf16 v[38:41], v[164:167], v[188:191], v[38:41]
	v_mfma_f32_16x16x32_bf16 v[34:37], v[172:175], v[188:191], v[34:37]
	v_mfma_f32_16x16x32_bf16 v[22:25], v[164:167], v[196:199], v[22:25]
	v_mfma_f32_16x16x32_bf16 v[18:21], v[172:175], v[196:199], v[18:21]
	v_mfma_f32_16x16x32_bf16 v[6:9], v[164:167], v[204:207], v[6:9]
	v_mfma_f32_16x16x32_bf16 v[2:5], v[172:175], v[204:207], v[2:5]
	v_mfma_f32_16x16x32_bf16 v[54:57], v[168:171], v[184:187], v[54:57]
	v_mfma_f32_16x16x32_bf16 v[50:53], v[176:179], v[184:187], v[50:53]
	v_mfma_f32_16x16x32_bf16 v[38:41], v[168:171], v[192:195], v[38:41]
	v_mfma_f32_16x16x32_bf16 v[34:37], v[176:179], v[192:195], v[34:37]
	v_mfma_f32_16x16x32_bf16 v[22:25], v[168:171], v[200:203], v[22:25]
	v_mfma_f32_16x16x32_bf16 v[18:21], v[176:179], v[200:203], v[18:21]
	v_mfma_f32_16x16x32_bf16 v[6:9], v[168:171], v[208:211], v[6:9]
	v_mfma_f32_16x16x32_bf16 v[2:5], v[176:179], v[208:211], v[2:5]
	s_setprio 0
	s_barrier
	s_add_i32 s72, s72, 2
	s_add_u32 s52, s52, 0x100
	s_addc_u32 s53, s53, 0
	s_add_u32 s70, s70, 0x100
	s_addc_u32 s71, s71, 0
	s_cmp_gt_u32 s72, 13
	s_cbranch_scc0 .LBB0_135
	s_and_b64 vcc, exec, s[42:43]
	s_cbranch_vccz .LBB0_138
	s_barrier

.LBB0_231:
	s_add_u32 s6, s0, 0xfffc0080
	s_addc_u32 s7, s1, -1
	s_add_i32 s24, 0, 0x10000
	s_cmp_eq_u32 s71, 12
	s_cselect_b32 s43, s37, s7
	s_cselect_b32 s42, s53, s6
	v_add_u32_e32 v0, s24, v177
	s_cselect_b32 s41, s51, s70
	s_cselect_b32 s40, s58, s59
	s_add_i32 s6, 0, 0x14000
	ds_read_b128 v[10:13], v0
	ds_read_b128 v[14:17], v0 offset:1024
	ds_read_b128 v[26:29], v0 offset:2048
	ds_read_b128 v[30:33], v0 offset:3072
	v_add_u32_e32 v0, s6, v177
	ds_read_b128 v[146:149], v0
	ds_read_b128 v[150:153], v0 offset:1024
	ds_read_b128 v[166:169], v0 offset:2048
	ds_read_b128 v[170:173], v0 offset:3072
	v_lshl_add_u64 v[174:175], s[0:1], 0, v[162:163]
	s_add_i32 m0, s63, 0xc000
	ds_read_b128 v[182:185], v180
	ds_read_b128 v[186:189], v180 offset:1024
	ds_read_b128 v[190:193], v180 offset:2048
	ds_read_b128 v[194:197], v180 offset:3072
	ds_read_b128 v[198:201], v180 offset:4096
	ds_read_b128 v[202:205], v180 offset:5120
	ds_read_b128 v[206:209], v180 offset:6144
	ds_read_b128 v[210:213], v180 offset:7168
	global_load_lds_dwordx4 v[174:175], off
	v_lshl_add_u64 v[174:175], s[0:1], 0, v[164:165]
	s_add_i32 m0, s63, 0xe000
	s_nop 0
	global_load_lds_dwordx4 v[174:175], off
	s_waitcnt vmcnt(8)
	s_waitcnt lgkmcnt(0)
	s_barrier
	s_setprio 1
	v_mfma_f32_16x16x32_bf16 v[142:145], v[10:13], v[182:185], v[142:145]
	v_mfma_f32_16x16x32_bf16 v[138:141], v[26:29], v[182:185], v[138:141]
	v_mfma_f32_16x16x32_bf16 v[126:129], v[10:13], v[190:193], v[126:129]
	v_mfma_f32_16x16x32_bf16 v[122:125], v[26:29], v[190:193], v[122:125]
	v_mfma_f32_16x16x32_bf16 v[110:113], v[10:13], v[198:201], v[110:113]
	v_mfma_f32_16x16x32_bf16 v[106:109], v[26:29], v[198:201], v[106:109]
	v_mfma_f32_16x16x32_bf16 v[94:97], v[10:13], v[206:209], v[94:97]
	v_mfma_f32_16x16x32_bf16 v[90:93], v[26:29], v[206:209], v[90:93]
	v_mfma_f32_16x16x32_bf16 v[142:145], v[14:17], v[186:189], v[142:145]
	v_mfma_f32_16x16x32_bf16 v[138:141], v[30:33], v[186:189], v[138:141]
	v_mfma_f32_16x16x32_bf16 v[126:129], v[14:17], v[194:197], v[126:129]
	v_mfma_f32_16x16x32_bf16 v[122:125], v[30:33], v[194:197], v[122:125]
	v_mfma_f32_16x16x32_bf16 v[110:113], v[14:17], v[202:205], v[110:113]
	v_mfma_f32_16x16x32_bf16 v[106:109], v[30:33], v[202:205], v[106:109]
	v_mfma_f32_16x16x32_bf16 v[94:97], v[14:17], v[210:213], v[94:97]
	v_mfma_f32_16x16x32_bf16 v[90:93], v[30:33], v[210:213], v[90:93]
	v_mfma_f32_16x16x32_bf16 v[134:137], v[146:149], v[182:185], v[134:137]
	v_mfma_f32_16x16x32_bf16 v[130:133], v[166:169], v[182:185], v[130:133]
	v_mfma_f32_16x16x32_bf16 v[118:121], v[146:149], v[190:193], v[118:121]
	v_mfma_f32_16x16x32_bf16 v[114:117], v[166:169], v[190:193], v[114:117]
	v_mfma_f32_16x16x32_bf16 v[102:105], v[146:149], v[198:201], v[102:105]
	v_mfma_f32_16x16x32_bf16 v[98:101], v[166:169], v[198:201], v[98:101]
	v_mfma_f32_16x16x32_bf16 v[86:89], v[146:149], v[206:209], v[86:89]
	v_mfma_f32_16x16x32_bf16 v[82:85], v[166:169], v[206:209], v[82:85]
	v_mfma_f32_16x16x32_bf16 v[134:137], v[150:153], v[186:189], v[134:137]
	v_mfma_f32_16x16x32_bf16 v[130:133], v[170:173], v[186:189], v[130:133]
	v_mfma_f32_16x16x32_bf16 v[118:121], v[150:153], v[194:197], v[118:121]
	v_mfma_f32_16x16x32_bf16 v[114:117], v[170:173], v[194:197], v[114:117]
	v_mfma_f32_16x16x32_bf16 v[102:105], v[150:153], v[202:205], v[102:105]
	v_mfma_f32_16x16x32_bf16 v[98:101], v[170:173], v[202:205], v[98:101]
	v_mfma_f32_16x16x32_bf16 v[86:89], v[150:153], v[210:213], v[86:89]
	v_mfma_f32_16x16x32_bf16 v[82:85], v[170:173], v[210:213], v[82:85]
	s_setprio 0
	s_barrier
	s_add_i32 s7, s24, s62
	v_lshl_add_u64 v[174:175], s[40:41], 0, v[158:159]
	s_mov_b32 m0, s7
	ds_read_b128 v[182:185], v180 offset:16384
	ds_read_b128 v[186:189], v180 offset:17408
	ds_read_b128 v[190:193], v180 offset:18432
	ds_read_b128 v[194:197], v180 offset:19456
	ds_read_b128 v[198:201], v180 offset:20480
	ds_read_b128 v[202:205], v180 offset:21504
	ds_read_b128 v[206:209], v180 offset:22528
	ds_read_b128 v[210:213], v180 offset:23552
	global_load_lds_dwordx4 v[174:175], off
	s_add_i32 m0, s7, 0x2000
	s_add_u32 s24, s40, 0x40000
	v_lshl_add_u64 v[214:215], s[40:41], 0, v[154:155]
	s_addc_u32 s25, s41, 0
	s_add_i32 s6, s6, s62
	global_load_lds_dwordx4 v[214:215], off
	v_lshl_add_u64 v[216:217], s[24:25], 0, v[158:159]
	s_mov_b32 m0, s6
	v_lshl_add_u64 v[218:219], s[42:43], 0, v[156:157]
	global_load_lds_dwordx4 v[216:217], off
	v_lshl_add_u64 v[216:217], s[24:25], 0, v[154:155]
	s_add_i32 m0, s6, 0x2000
	s_nop 0
	global_load_lds_dwordx4 v[216:217], off
	v_lshl_add_u64 v[216:217], s[42:43], 0, v[160:161]
	s_mov_b32 m0, s63
	s_nop 0
	global_load_lds_dwordx4 v[216:217], off
	s_mov_b32 m0, s64
	s_nop 0
	global_load_lds_dwordx4 v[218:219], off
	s_waitcnt vmcnt(8)
	s_waitcnt lgkmcnt(0)
	s_barrier
	s_setprio 1
	v_mfma_f32_16x16x32_bf16 v[78:81], v[10:13], v[182:185], v[78:81]
	v_mfma_f32_16x16x32_bf16 v[74:77], v[26:29], v[182:185], v[74:77]
	v_mfma_f32_16x16x32_bf16 v[62:65], v[10:13], v[190:193], v[62:65]
	v_mfma_f32_16x16x32_bf16 v[58:61], v[26:29], v[190:193], v[58:61]
	v_mfma_f32_16x16x32_bf16 v[46:49], v[10:13], v[198:201], v[46:49]
	v_mfma_f32_16x16x32_bf16 v[42:45], v[26:29], v[198:201], v[42:45]
	v_mfma_f32_16x16x32_bf16 v[10:13], v[10:13], v[206:209], v[22:25]
	v_mfma_f32_16x16x32_bf16 v[78:81], v[14:17], v[186:189], v[78:81]
	v_mfma_f32_16x16x32_bf16 v[74:77], v[30:33], v[186:189], v[74:77]
	v_mfma_f32_16x16x32_bf16 v[62:65], v[14:17], v[194:197], v[62:65]
	v_mfma_f32_16x16x32_bf16 v[58:61], v[30:33], v[194:197], v[58:61]
	v_mfma_f32_16x16x32_bf16 v[46:49], v[14:17], v[202:205], v[46:49]
	v_mfma_f32_16x16x32_bf16 v[42:45], v[30:33], v[202:205], v[42:45]
	v_mfma_f32_16x16x32_bf16 v[10:13], v[14:17], v[210:213], v[10:13]
	v_mfma_f32_16x16x32_bf16 v[14:17], v[26:29], v[206:209], v[18:21]
	v_mfma_f32_16x16x32_bf16 v[14:17], v[30:33], v[210:213], v[14:17]
	v_mfma_f32_16x16x32_bf16 v[18:21], v[146:149], v[182:185], v[70:73]
	v_mfma_f32_16x16x32_bf16 v[26:29], v[150:153], v[186:189], v[18:21]
	v_mfma_f32_16x16x32_bf16 v[18:21], v[166:169], v[182:185], v[66:69]
	v_mfma_f32_16x16x32_bf16 v[30:33], v[170:173], v[186:189], v[18:21]
	v_mfma_f32_16x16x32_bf16 v[18:21], v[146:149], v[190:193], v[54:57]
	v_mfma_f32_16x16x32_bf16 v[54:57], v[150:153], v[194:197], v[18:21]
	v_mfma_f32_16x16x32_bf16 v[18:21], v[166:169], v[190:193], v[50:53]
	v_mfma_f32_16x16x32_bf16 v[50:53], v[170:173], v[194:197], v[18:21]
	v_mfma_f32_16x16x32_bf16 v[18:21], v[146:149], v[198:201], v[38:41]
	v_mfma_f32_16x16x32_bf16 v[38:41], v[150:153], v[202:205], v[18:21]
	v_mfma_f32_16x16x32_bf16 v[18:21], v[166:169], v[198:201], v[34:37]
	v_mfma_f32_16x16x32_bf16 v[6:9], v[146:149], v[206:209], v[6:9]
	v_mfma_f32_16x16x32_bf16 v[2:5], v[166:169], v[206:209], v[2:5]
	v_mfma_f32_16x16x32_bf16 v[34:37], v[170:173], v[202:205], v[18:21]
	v_mfma_f32_16x16x32_bf16 v[6:9], v[150:153], v[210:213], v[6:9]
	v_mfma_f32_16x16x32_bf16 v[2:5], v[170:173], v[210:213], v[2:5]
	s_setprio 0
	s_barrier
	s_add_i32 s6, 0, 0x18000
	v_add_u32_e32 v0, s6, v177
	s_add_i32 s7, 0, 0x1c000
	ds_read_b128 v[18:21], v0
	ds_read_b128 v[22:25], v0 offset:1024
	ds_read_b128 v[66:69], v0 offset:2048
	ds_read_b128 v[70:73], v0 offset:3072
	v_add_u32_e32 v0, s7, v177
	ds_read_b128 v[146:149], v0
	ds_read_b128 v[150:153], v0 offset:1024
	ds_read_b128 v[166:169], v0 offset:2048
	ds_read_b128 v[170:173], v0 offset:3072
	s_add_u32 s24, s42, 0x40000
	s_addc_u32 s25, s43, 0
	s_mov_b32 m0, s65
	v_lshl_add_u64 v[220:221], s[24:25], 0, v[160:161]
	ds_read_b128 v[182:185], v180 offset:32768
	ds_read_b128 v[186:189], v180 offset:33792
	ds_read_b128 v[190:193], v180 offset:34816
	ds_read_b128 v[194:197], v180 offset:35840
	ds_read_b128 v[198:201], v180 offset:36864
	ds_read_b128 v[202:205], v180 offset:37888
	ds_read_b128 v[206:209], v180 offset:38912
	ds_read_b128 v[210:213], v180 offset:39936
	global_load_lds_dwordx4 v[220:221], off
	v_lshl_add_u64 v[220:221], s[24:25], 0, v[156:157]
	s_mov_b32 m0, s66
	s_nop 0
	global_load_lds_dwordx4 v[220:221], off
	s_waitcnt vmcnt(8)
	s_waitcnt lgkmcnt(0)
	s_barrier
	s_setprio 1
	v_mfma_f32_16x16x32_bf16 v[142:145], v[18:21], v[182:185], v[142:145]
	v_mfma_f32_16x16x32_bf16 v[138:141], v[66:69], v[182:185], v[138:141]
	v_mfma_f32_16x16x32_bf16 v[126:129], v[18:21], v[190:193], v[126:129]
	v_mfma_f32_16x16x32_bf16 v[122:125], v[66:69], v[190:193], v[122:125]
	v_mfma_f32_16x16x32_bf16 v[110:113], v[18:21], v[198:201], v[110:113]
	v_mfma_f32_16x16x32_bf16 v[106:109], v[66:69], v[198:201], v[106:109]
	v_mfma_f32_16x16x32_bf16 v[94:97], v[18:21], v[206:209], v[94:97]
	v_mfma_f32_16x16x32_bf16 v[90:93], v[66:69], v[206:209], v[90:93]
	v_mfma_f32_16x16x32_bf16 v[142:145], v[22:25], v[186:189], v[142:145]
	v_mfma_f32_16x16x32_bf16 v[138:141], v[70:73], v[186:189], v[138:141]
	v_mfma_f32_16x16x32_bf16 v[126:129], v[22:25], v[194:197], v[126:129]
	v_mfma_f32_16x16x32_bf16 v[122:125], v[70:73], v[194:197], v[122:125]
	v_mfma_f32_16x16x32_bf16 v[110:113], v[22:25], v[202:205], v[110:113]
	v_mfma_f32_16x16x32_bf16 v[106:109], v[70:73], v[202:205], v[106:109]
	v_mfma_f32_16x16x32_bf16 v[94:97], v[22:25], v[210:213], v[94:97]
	v_mfma_f32_16x16x32_bf16 v[90:93], v[70:73], v[210:213], v[90:93]
	v_mfma_f32_16x16x32_bf16 v[134:137], v[146:149], v[182:185], v[134:137]
	v_mfma_f32_16x16x32_bf16 v[130:133], v[166:169], v[182:185], v[130:133]
	v_mfma_f32_16x16x32_bf16 v[118:121], v[146:149], v[190:193], v[118:121]
	v_mfma_f32_16x16x32_bf16 v[114:117], v[166:169], v[190:193], v[114:117]
	v_mfma_f32_16x16x32_bf16 v[102:105], v[146:149], v[198:201], v[102:105]
	v_mfma_f32_16x16x32_bf16 v[98:101], v[166:169], v[198:201], v[98:101]
	v_mfma_f32_16x16x32_bf16 v[86:89], v[146:149], v[206:209], v[86:89]
	v_mfma_f32_16x16x32_bf16 v[82:85], v[166:169], v[206:209], v[82:85]
	v_mfma_f32_16x16x32_bf16 v[134:137], v[150:153], v[186:189], v[134:137]
	v_mfma_f32_16x16x32_bf16 v[130:133], v[170:173], v[186:189], v[130:133]
	v_mfma_f32_16x16x32_bf16 v[118:121], v[150:153], v[194:197], v[118:121]
	v_mfma_f32_16x16x32_bf16 v[114:117], v[170:173], v[194:197], v[114:117]
	v_mfma_f32_16x16x32_bf16 v[102:105], v[150:153], v[202:205], v[102:105]
	v_mfma_f32_16x16x32_bf16 v[98:101], v[170:173], v[202:205], v[98:101]
	v_mfma_f32_16x16x32_bf16 v[86:89], v[150:153], v[210:213], v[86:89]
	v_mfma_f32_16x16x32_bf16 v[82:85], v[170:173], v[210:213], v[82:85]
	s_setprio 0
	s_barrier
	s_add_i32 s6, s6, s62
	v_lshl_add_u64 v[174:175], v[174:175], 0, s[84:85]
	s_mov_b32 m0, s6
	ds_read_b128 v[182:185], v180 offset:49152
	ds_read_b128 v[186:189], v180 offset:50176
	ds_read_b128 v[190:193], v180 offset:51200
	ds_read_b128 v[194:197], v180 offset:52224
	ds_read_b128 v[198:201], v180 offset:53248
	ds_read_b128 v[202:205], v180 offset:54272
	ds_read_b128 v[206:209], v180 offset:55296
	ds_read_b128 v[210:213], v180 offset:56320
	global_load_lds_dwordx4 v[174:175], off
	s_add_i32 m0, s6, 0x2000
	s_add_u32 s24, s40, 0x40080
	v_lshl_add_u64 v[174:175], v[214:215], 0, s[84:85]
	s_addc_u32 s25, s41, 0
	s_add_i32 s6, s7, s62
	global_load_lds_dwordx4 v[174:175], off
	v_lshl_add_u64 v[174:175], s[24:25], 0, v[158:159]
	s_mov_b32 m0, s6
	s_nop 0
	global_load_lds_dwordx4 v[174:175], off
	v_lshl_add_u64 v[174:175], s[24:25], 0, v[154:155]
	s_add_i32 m0, s6, 0x2000
	s_nop 0
	global_load_lds_dwordx4 v[174:175], off
	v_lshl_add_u64 v[174:175], v[216:217], 0, s[84:85]
	s_mov_b32 m0, s8
	s_nop 0
	global_load_lds_dwordx4 v[174:175], off
	v_lshl_add_u64 v[174:175], v[218:219], 0, s[84:85]
	s_mov_b32 m0, s67
	s_nop 0
	global_load_lds_dwordx4 v[174:175], off
	s_waitcnt vmcnt(8)
	s_waitcnt lgkmcnt(0)
	s_barrier
	s_setprio 1
	v_mfma_f32_16x16x32_bf16 v[78:81], v[18:21], v[182:185], v[78:81]
	v_mfma_f32_16x16x32_bf16 v[62:65], v[18:21], v[190:193], v[62:65]
	v_mfma_f32_16x16x32_bf16 v[46:49], v[18:21], v[198:201], v[46:49]
	v_mfma_f32_16x16x32_bf16 v[10:13], v[18:21], v[206:209], v[10:13]
	v_mfma_f32_16x16x32_bf16 v[78:81], v[22:25], v[186:189], v[78:81]
	v_mfma_f32_16x16x32_bf16 v[74:77], v[66:69], v[182:185], v[74:77]
	v_mfma_f32_16x16x32_bf16 v[62:65], v[22:25], v[194:197], v[62:65]
	v_mfma_f32_16x16x32_bf16 v[58:61], v[66:69], v[190:193], v[58:61]
	v_mfma_f32_16x16x32_bf16 v[46:49], v[22:25], v[202:205], v[46:49]
	v_mfma_f32_16x16x32_bf16 v[42:45], v[66:69], v[198:201], v[42:45]
	v_mfma_f32_16x16x32_bf16 v[22:25], v[22:25], v[210:213], v[10:13]
	v_mfma_f32_16x16x32_bf16 v[10:13], v[66:69], v[206:209], v[14:17]
	v_mfma_f32_16x16x32_bf16 v[74:77], v[70:73], v[186:189], v[74:77]
	v_mfma_f32_16x16x32_bf16 v[58:61], v[70:73], v[194:197], v[58:61]
	v_mfma_f32_16x16x32_bf16 v[42:45], v[70:73], v[202:205], v[42:45]
	v_mfma_f32_16x16x32_bf16 v[18:21], v[70:73], v[210:213], v[10:13]
	v_mfma_f32_16x16x32_bf16 v[10:13], v[146:149], v[182:185], v[26:29]
	v_mfma_f32_16x16x32_bf16 v[70:73], v[150:153], v[186:189], v[10:13]
	v_mfma_f32_16x16x32_bf16 v[10:13], v[166:169], v[182:185], v[30:33]
	v_mfma_f32_16x16x32_bf16 v[66:69], v[170:173], v[186:189], v[10:13]
	v_mfma_f32_16x16x32_bf16 v[10:13], v[146:149], v[190:193], v[54:57]
	v_mfma_f32_16x16x32_bf16 v[54:57], v[150:153], v[194:197], v[10:13]
	v_mfma_f32_16x16x32_bf16 v[10:13], v[166:169], v[190:193], v[50:53]
	v_mfma_f32_16x16x32_bf16 v[50:53], v[170:173], v[194:197], v[10:13]
	v_mfma_f32_16x16x32_bf16 v[10:13], v[146:149], v[198:201], v[38:41]
	v_mfma_f32_16x16x32_bf16 v[38:41], v[150:153], v[202:205], v[10:13]
	v_mfma_f32_16x16x32_bf16 v[10:13], v[166:169], v[198:201], v[34:37]
	v_mfma_f32_16x16x32_bf16 v[6:9], v[146:149], v[206:209], v[6:9]
	v_mfma_f32_16x16x32_bf16 v[2:5], v[166:169], v[206:209], v[2:5]
	v_mfma_f32_16x16x32_bf16 v[34:37], v[170:173], v[202:205], v[10:13]
	v_mfma_f32_16x16x32_bf16 v[6:9], v[150:153], v[210:213], v[6:9]
	v_mfma_f32_16x16x32_bf16 v[2:5], v[170:173], v[210:213], v[2:5]
	s_setprio 0
	s_barrier
	s_add_i32 s71, s71, 2
	s_add_u32 s0, s0, 0x100
	s_addc_u32 s1, s1, 0
	s_add_u32 s59, s59, 0x100
	s_addc_u32 s70, s70, 0
	s_cmp_gt_u32 s71, 13
	s_cbranch_scc0 .LBB0_231
	s_and_b64 vcc, exec, s[48:49]
	s_cbranch_vccz .LBB0_234
	s_barrier

.LBB0_560:
	s_add_u32 s6, s40, 0xfffc0080
	s_addc_u32 s7, s41, -1
	s_add_i32 s24, 0, 0x10000
	s_cmp_eq_u32 s66, 12
	s_cselect_b32 s53, s47, s7
	s_cselect_b32 s52, s62, s6
	v_add_u32_e32 v0, s24, v193
	s_cselect_b32 s43, s45, s65
	s_cselect_b32 s42, s63, s64
	s_add_i32 s6, 0, 0x14000
	ds_read_b128 v[74:77], v0
	ds_read_b128 v[86:89], v0 offset:1024
	ds_read_b128 v[98:101], v0 offset:2048
	ds_read_b128 v[102:105], v0 offset:3072
	v_add_u32_e32 v0, s6, v193
	ds_read_b128 v[118:121], v0
	ds_read_b128 v[126:129], v0 offset:1024
	ds_read_b128 v[138:141], v0 offset:2048
	ds_read_b128 v[142:145], v0 offset:3072
	v_lshl_add_u64 v[188:189], s[40:41], 0, v[180:181]
	s_add_i32 m0, s55, 0xc000
	ds_read_b128 v[154:157], v213
	ds_read_b128 v[162:165], v213 offset:1024
	ds_read_b128 v[184:187], v213 offset:2048
	ds_read_b128 v[194:197], v213 offset:3072
	ds_read_b128 v[198:201], v213 offset:4096
	ds_read_b128 v[214:217], v213 offset:5120
	ds_read_b128 v[218:221], v213 offset:6144
	ds_read_b128 v[222:225], v213 offset:7168
	global_load_lds_dwordx4 v[188:189], off
	v_lshl_add_u64 v[188:189], s[40:41], 0, v[182:183]
	s_add_i32 m0, s55, 0xe000
	s_nop 0
	global_load_lds_dwordx4 v[188:189], off
	s_waitcnt vmcnt(8)
	s_waitcnt lgkmcnt(0)
	s_barrier
	s_setprio 1
	v_mfma_f32_16x16x32_bf16 v[166:169], v[74:77], v[154:157], v[166:169]
	v_mfma_f32_16x16x32_bf16 v[158:161], v[98:101], v[154:157], v[158:161]
	v_mfma_f32_16x16x32_bf16 v[134:137], v[74:77], v[184:187], v[134:137]
	v_mfma_f32_16x16x32_bf16 v[130:133], v[98:101], v[184:187], v[130:133]
	v_mfma_f32_16x16x32_bf16 v[110:113], v[74:77], v[198:201], v[110:113]
	v_mfma_f32_16x16x32_bf16 v[106:109], v[98:101], v[198:201], v[106:109]
	v_mfma_f32_16x16x32_bf16 v[82:85], v[74:77], v[218:221], v[82:85]
	v_mfma_f32_16x16x32_bf16 v[78:81], v[98:101], v[218:221], v[78:81]
	v_mfma_f32_16x16x32_bf16 v[166:169], v[86:89], v[162:165], v[166:169]
	v_mfma_f32_16x16x32_bf16 v[158:161], v[102:105], v[162:165], v[158:161]
	v_mfma_f32_16x16x32_bf16 v[134:137], v[86:89], v[194:197], v[134:137]
	v_mfma_f32_16x16x32_bf16 v[130:133], v[102:105], v[194:197], v[130:133]
	v_mfma_f32_16x16x32_bf16 v[110:113], v[86:89], v[214:217], v[110:113]
	v_mfma_f32_16x16x32_bf16 v[106:109], v[102:105], v[214:217], v[106:109]
	v_mfma_f32_16x16x32_bf16 v[82:85], v[86:89], v[222:225], v[82:85]
	v_mfma_f32_16x16x32_bf16 v[78:81], v[102:105], v[222:225], v[78:81]
	v_mfma_f32_16x16x32_bf16 v[150:153], v[118:121], v[154:157], v[150:153]
	v_mfma_f32_16x16x32_bf16 v[146:149], v[138:141], v[154:157], v[146:149]
	v_mfma_f32_16x16x32_bf16 v[122:125], v[118:121], v[184:187], v[122:125]
	v_mfma_f32_16x16x32_bf16 v[114:117], v[138:141], v[184:187], v[114:117]
	v_mfma_f32_16x16x32_bf16 v[94:97], v[118:121], v[198:201], v[94:97]
	v_mfma_f32_16x16x32_bf16 v[90:93], v[138:141], v[198:201], v[90:93]
	v_mfma_f32_16x16x32_bf16 v[70:73], v[118:121], v[218:221], v[70:73]
	v_mfma_f32_16x16x32_bf16 v[66:69], v[138:141], v[218:221], v[66:69]
	v_mfma_f32_16x16x32_bf16 v[150:153], v[126:129], v[162:165], v[150:153]
	v_mfma_f32_16x16x32_bf16 v[146:149], v[142:145], v[162:165], v[146:149]
	v_mfma_f32_16x16x32_bf16 v[122:125], v[126:129], v[194:197], v[122:125]
	v_mfma_f32_16x16x32_bf16 v[114:117], v[142:145], v[194:197], v[114:117]
	v_mfma_f32_16x16x32_bf16 v[94:97], v[126:129], v[214:217], v[94:97]
	v_mfma_f32_16x16x32_bf16 v[90:93], v[142:145], v[214:217], v[90:93]
	v_mfma_f32_16x16x32_bf16 v[70:73], v[126:129], v[222:225], v[70:73]
	v_mfma_f32_16x16x32_bf16 v[66:69], v[142:145], v[222:225], v[66:69]
	s_setprio 0
	s_barrier
	s_add_i32 s7, s24, s54
	v_lshl_add_u64 v[188:189], s[42:43], 0, v[174:175]
	s_mov_b32 m0, s7
	ds_read_b128 v[154:157], v213 offset:16384
	ds_read_b128 v[162:165], v213 offset:17408
	ds_read_b128 v[184:187], v213 offset:18432
	ds_read_b128 v[194:197], v213 offset:19456
	ds_read_b128 v[198:201], v213 offset:20480
	ds_read_b128 v[214:217], v213 offset:21504
	ds_read_b128 v[218:221], v213 offset:22528
	ds_read_b128 v[222:225], v213 offset:23552
	global_load_lds_dwordx4 v[188:189], off
	s_add_i32 m0, s7, 0x2000
	s_add_u32 s24, s42, 0x40000
	v_lshl_add_u64 v[202:203], s[42:43], 0, v[170:171]
	s_addc_u32 s25, s43, 0
	s_add_i32 s6, s6, s54
	global_load_lds_dwordx4 v[202:203], off
	v_lshl_add_u64 v[226:227], s[24:25], 0, v[174:175]
	s_mov_b32 m0, s6
	v_lshl_add_u64 v[230:231], s[52:53], 0, v[172:173]
	global_load_lds_dwordx4 v[226:227], off
	v_lshl_add_u64 v[226:227], s[24:25], 0, v[170:171]
	s_add_i32 m0, s6, 0x2000
	s_nop 0
	global_load_lds_dwordx4 v[226:227], off
	v_lshl_add_u64 v[226:227], s[52:53], 0, v[176:177]
	s_mov_b32 m0, s55
	s_nop 0
	global_load_lds_dwordx4 v[226:227], off
	s_mov_b32 m0, s56
	s_nop 0
	global_load_lds_dwordx4 v[230:231], off
	s_waitcnt vmcnt(8)
	s_waitcnt lgkmcnt(0)
	s_barrier
	s_setprio 1
	v_mfma_f32_16x16x32_bf16 v[62:65], v[74:77], v[154:157], v[62:65]
	v_mfma_f32_16x16x32_bf16 v[58:61], v[98:101], v[154:157], v[58:61]
	v_mfma_f32_16x16x32_bf16 v[46:49], v[74:77], v[184:187], v[46:49]
	v_mfma_f32_16x16x32_bf16 v[42:45], v[98:101], v[184:187], v[42:45]
	v_mfma_f32_16x16x32_bf16 v[30:33], v[74:77], v[198:201], v[30:33]
	v_mfma_f32_16x16x32_bf16 v[26:29], v[98:101], v[198:201], v[26:29]
	v_mfma_f32_16x16x32_bf16 v[14:17], v[74:77], v[218:221], v[14:17]
	v_mfma_f32_16x16x32_bf16 v[10:13], v[98:101], v[218:221], v[10:13]
	v_mfma_f32_16x16x32_bf16 v[62:65], v[86:89], v[162:165], v[62:65]
	v_mfma_f32_16x16x32_bf16 v[58:61], v[102:105], v[162:165], v[58:61]
	v_mfma_f32_16x16x32_bf16 v[46:49], v[86:89], v[194:197], v[46:49]
	v_mfma_f32_16x16x32_bf16 v[42:45], v[102:105], v[194:197], v[42:45]
	v_mfma_f32_16x16x32_bf16 v[30:33], v[86:89], v[214:217], v[30:33]
	v_mfma_f32_16x16x32_bf16 v[26:29], v[102:105], v[214:217], v[26:29]
	v_mfma_f32_16x16x32_bf16 v[14:17], v[86:89], v[222:225], v[14:17]
	v_mfma_f32_16x16x32_bf16 v[10:13], v[102:105], v[222:225], v[10:13]
	v_mfma_f32_16x16x32_bf16 v[54:57], v[118:121], v[154:157], v[54:57]
	v_mfma_f32_16x16x32_bf16 v[50:53], v[138:141], v[154:157], v[50:53]
	v_mfma_f32_16x16x32_bf16 v[38:41], v[118:121], v[184:187], v[38:41]
	v_mfma_f32_16x16x32_bf16 v[34:37], v[138:141], v[184:187], v[34:37]
	v_mfma_f32_16x16x32_bf16 v[22:25], v[118:121], v[198:201], v[22:25]
	v_mfma_f32_16x16x32_bf16 v[18:21], v[138:141], v[198:201], v[18:21]
	v_mfma_f32_16x16x32_bf16 v[6:9], v[118:121], v[218:221], v[6:9]
	v_mfma_f32_16x16x32_bf16 v[2:5], v[138:141], v[218:221], v[2:5]
	v_mfma_f32_16x16x32_bf16 v[54:57], v[126:129], v[162:165], v[54:57]
	v_mfma_f32_16x16x32_bf16 v[50:53], v[142:145], v[162:165], v[50:53]
	v_mfma_f32_16x16x32_bf16 v[38:41], v[126:129], v[194:197], v[38:41]
	v_mfma_f32_16x16x32_bf16 v[34:37], v[142:145], v[194:197], v[34:37]
	v_mfma_f32_16x16x32_bf16 v[22:25], v[126:129], v[214:217], v[22:25]
	v_mfma_f32_16x16x32_bf16 v[18:21], v[142:145], v[214:217], v[18:21]
	v_mfma_f32_16x16x32_bf16 v[6:9], v[126:129], v[222:225], v[6:9]
	v_mfma_f32_16x16x32_bf16 v[2:5], v[142:145], v[222:225], v[2:5]
	s_setprio 0
	s_barrier
	s_add_i32 s6, 0, 0x18000
	v_add_u32_e32 v0, s6, v193
	s_add_i32 s7, 0, 0x1c000
	ds_read_b128 v[74:77], v0
	ds_read_b128 v[86:89], v0 offset:1024
	ds_read_b128 v[98:101], v0 offset:2048
	ds_read_b128 v[102:105], v0 offset:3072
	v_add_u32_e32 v0, s7, v193
	ds_read_b128 v[118:121], v0
	ds_read_b128 v[126:129], v0 offset:1024
	ds_read_b128 v[138:141], v0 offset:2048
	ds_read_b128 v[142:145], v0 offset:3072
	s_add_u32 s24, s52, 0x40000
	s_addc_u32 s25, s53, 0
	s_mov_b32 m0, s57
	v_lshl_add_u64 v[232:233], s[24:25], 0, v[176:177]
	ds_read_b128 v[154:157], v213 offset:32768
	ds_read_b128 v[162:165], v213 offset:33792
	ds_read_b128 v[184:187], v213 offset:34816
	ds_read_b128 v[194:197], v213 offset:35840
	ds_read_b128 v[198:201], v213 offset:36864
	ds_read_b128 v[214:217], v213 offset:37888
	ds_read_b128 v[218:221], v213 offset:38912
	ds_read_b128 v[222:225], v213 offset:39936
	global_load_lds_dwordx4 v[232:233], off
	v_lshl_add_u64 v[232:233], s[24:25], 0, v[172:173]
	s_mov_b32 m0, s58
	s_nop 0
	global_load_lds_dwordx4 v[232:233], off
	s_waitcnt vmcnt(8)
	s_waitcnt lgkmcnt(0)
	s_barrier
	s_setprio 1
	v_mfma_f32_16x16x32_bf16 v[166:169], v[74:77], v[154:157], v[166:169]
	v_mfma_f32_16x16x32_bf16 v[158:161], v[98:101], v[154:157], v[158:161]
	v_mfma_f32_16x16x32_bf16 v[134:137], v[74:77], v[184:187], v[134:137]
	v_mfma_f32_16x16x32_bf16 v[130:133], v[98:101], v[184:187], v[130:133]
	v_mfma_f32_16x16x32_bf16 v[110:113], v[74:77], v[198:201], v[110:113]
	v_mfma_f32_16x16x32_bf16 v[106:109], v[98:101], v[198:201], v[106:109]
	v_mfma_f32_16x16x32_bf16 v[82:85], v[74:77], v[218:221], v[82:85]
	v_mfma_f32_16x16x32_bf16 v[78:81], v[98:101], v[218:221], v[78:81]
	v_mfma_f32_16x16x32_bf16 v[166:169], v[86:89], v[162:165], v[166:169]
	v_mfma_f32_16x16x32_bf16 v[158:161], v[102:105], v[162:165], v[158:161]
	v_mfma_f32_16x16x32_bf16 v[134:137], v[86:89], v[194:197], v[134:137]
	v_mfma_f32_16x16x32_bf16 v[130:133], v[102:105], v[194:197], v[130:133]
	v_mfma_f32_16x16x32_bf16 v[110:113], v[86:89], v[214:217], v[110:113]
	v_mfma_f32_16x16x32_bf16 v[106:109], v[102:105], v[214:217], v[106:109]
	v_mfma_f32_16x16x32_bf16 v[82:85], v[86:89], v[222:225], v[82:85]
	v_mfma_f32_16x16x32_bf16 v[78:81], v[102:105], v[222:225], v[78:81]
	v_mfma_f32_16x16x32_bf16 v[150:153], v[118:121], v[154:157], v[150:153]
	v_mfma_f32_16x16x32_bf16 v[146:149], v[138:141], v[154:157], v[146:149]
	v_mfma_f32_16x16x32_bf16 v[122:125], v[118:121], v[184:187], v[122:125]
	v_mfma_f32_16x16x32_bf16 v[114:117], v[138:141], v[184:187], v[114:117]
	v_mfma_f32_16x16x32_bf16 v[94:97], v[118:121], v[198:201], v[94:97]
	v_mfma_f32_16x16x32_bf16 v[90:93], v[138:141], v[198:201], v[90:93]
	v_mfma_f32_16x16x32_bf16 v[70:73], v[118:121], v[218:221], v[70:73]
	v_mfma_f32_16x16x32_bf16 v[66:69], v[138:141], v[218:221], v[66:69]
	v_mfma_f32_16x16x32_bf16 v[150:153], v[126:129], v[162:165], v[150:153]
	v_mfma_f32_16x16x32_bf16 v[146:149], v[142:145], v[162:165], v[146:149]
	v_mfma_f32_16x16x32_bf16 v[122:125], v[126:129], v[194:197], v[122:125]
	v_mfma_f32_16x16x32_bf16 v[114:117], v[142:145], v[194:197], v[114:117]
	v_mfma_f32_16x16x32_bf16 v[94:97], v[126:129], v[214:217], v[94:97]
	v_mfma_f32_16x16x32_bf16 v[90:93], v[142:145], v[214:217], v[90:93]
	v_mfma_f32_16x16x32_bf16 v[70:73], v[126:129], v[222:225], v[70:73]
	v_mfma_f32_16x16x32_bf16 v[66:69], v[142:145], v[222:225], v[66:69]
	s_setprio 0
	s_barrier
	s_add_i32 s6, s6, s54
	v_lshl_add_u64 v[188:189], v[188:189], 0, s[84:85]
	s_mov_b32 m0, s6
	ds_read_b128 v[154:157], v213 offset:49152
	ds_read_b128 v[162:165], v213 offset:50176
	ds_read_b128 v[184:187], v213 offset:51200
	ds_read_b128 v[194:197], v213 offset:52224
	ds_read_b128 v[198:201], v213 offset:53248
	ds_read_b128 v[214:217], v213 offset:54272
	ds_read_b128 v[218:221], v213 offset:55296
	ds_read_b128 v[222:225], v213 offset:56320
	global_load_lds_dwordx4 v[188:189], off
	s_add_i32 m0, s6, 0x2000
	s_add_u32 s24, s42, 0x40080
	v_lshl_add_u64 v[188:189], v[202:203], 0, s[84:85]
	s_addc_u32 s25, s43, 0
	s_add_i32 s6, s7, s54
	global_load_lds_dwordx4 v[188:189], off
	v_lshl_add_u64 v[188:189], s[24:25], 0, v[174:175]
	s_mov_b32 m0, s6
	s_nop 0
	global_load_lds_dwordx4 v[188:189], off
	v_lshl_add_u64 v[188:189], s[24:25], 0, v[170:171]
	s_add_i32 m0, s6, 0x2000
	s_nop 0
	global_load_lds_dwordx4 v[188:189], off
	v_lshl_add_u64 v[188:189], v[226:227], 0, s[84:85]
	s_mov_b32 m0, s59
	s_nop 0
	global_load_lds_dwordx4 v[188:189], off
	v_lshl_add_u64 v[188:189], v[230:231], 0, s[84:85]
	s_mov_b32 m0, s60
	s_nop 0
	global_load_lds_dwordx4 v[188:189], off
	s_waitcnt vmcnt(8)
	s_waitcnt lgkmcnt(0)
	s_barrier
	s_setprio 1
	v_mfma_f32_16x16x32_bf16 v[62:65], v[74:77], v[154:157], v[62:65]
	v_mfma_f32_16x16x32_bf16 v[58:61], v[98:101], v[154:157], v[58:61]
	v_mfma_f32_16x16x32_bf16 v[46:49], v[74:77], v[184:187], v[46:49]
	v_mfma_f32_16x16x32_bf16 v[42:45], v[98:101], v[184:187], v[42:45]
	v_mfma_f32_16x16x32_bf16 v[30:33], v[74:77], v[198:201], v[30:33]
	v_mfma_f32_16x16x32_bf16 v[26:29], v[98:101], v[198:201], v[26:29]
	v_mfma_f32_16x16x32_bf16 v[14:17], v[74:77], v[218:221], v[14:17]
	v_mfma_f32_16x16x32_bf16 v[10:13], v[98:101], v[218:221], v[10:13]
	v_mfma_f32_16x16x32_bf16 v[62:65], v[86:89], v[162:165], v[62:65]
	v_mfma_f32_16x16x32_bf16 v[58:61], v[102:105], v[162:165], v[58:61]
	v_mfma_f32_16x16x32_bf16 v[46:49], v[86:89], v[194:197], v[46:49]
	v_mfma_f32_16x16x32_bf16 v[42:45], v[102:105], v[194:197], v[42:45]
	v_mfma_f32_16x16x32_bf16 v[30:33], v[86:89], v[214:217], v[30:33]
	v_mfma_f32_16x16x32_bf16 v[26:29], v[102:105], v[214:217], v[26:29]
	v_mfma_f32_16x16x32_bf16 v[14:17], v[86:89], v[222:225], v[14:17]
	v_mfma_f32_16x16x32_bf16 v[10:13], v[102:105], v[222:225], v[10:13]
	v_mfma_f32_16x16x32_bf16 v[54:57], v[118:121], v[154:157], v[54:57]
	v_mfma_f32_16x16x32_bf16 v[50:53], v[138:141], v[154:157], v[50:53]
	v_mfma_f32_16x16x32_bf16 v[38:41], v[118:121], v[184:187], v[38:41]
	v_mfma_f32_16x16x32_bf16 v[34:37], v[138:141], v[184:187], v[34:37]
	v_mfma_f32_16x16x32_bf16 v[22:25], v[118:121], v[198:201], v[22:25]
	v_mfma_f32_16x16x32_bf16 v[18:21], v[138:141], v[198:201], v[18:21]
	v_mfma_f32_16x16x32_bf16 v[6:9], v[118:121], v[218:221], v[6:9]
	v_mfma_f32_16x16x32_bf16 v[2:5], v[138:141], v[218:221], v[2:5]
	v_mfma_f32_16x16x32_bf16 v[54:57], v[126:129], v[162:165], v[54:57]
	v_mfma_f32_16x16x32_bf16 v[50:53], v[142:145], v[162:165], v[50:53]
	v_mfma_f32_16x16x32_bf16 v[38:41], v[126:129], v[194:197], v[38:41]
	v_mfma_f32_16x16x32_bf16 v[34:37], v[142:145], v[194:197], v[34:37]
	v_mfma_f32_16x16x32_bf16 v[22:25], v[126:129], v[214:217], v[22:25]
	v_mfma_f32_16x16x32_bf16 v[18:21], v[142:145], v[214:217], v[18:21]
	v_mfma_f32_16x16x32_bf16 v[6:9], v[126:129], v[222:225], v[6:9]
	v_mfma_f32_16x16x32_bf16 v[2:5], v[142:145], v[222:225], v[2:5]
	s_setprio 0
	s_barrier
	s_add_i32 s66, s66, 2
	s_add_u32 s40, s40, 0x100
	s_addc_u32 s41, s41, 0
	s_add_u32 s64, s64, 0x100
	s_addc_u32 s65, s65, 0
	s_cmp_gt_u32 s66, 13
	s_cbranch_scc0 .LBB0_560
	s_and_b64 vcc, exec, s[26:27]
	s_cbranch_vccz .LBB0_563
	s_barrier

.LBB0_763:
	s_add_i32 s25, s24, 2
	s_add_u32 s6, s50, 0x80
	s_addc_u32 s7, s51, 0
	s_add_i32 s55, 0, 0x10000
	s_cmp_eq_u32 s67, s24
	s_cselect_b32 s53, s41, s7
	s_cselect_b32 s52, s40, s6
	s_cselect_b32 s7, s49, s54
	s_cselect_b32 s6, s48, s37
	s_add_i32 s24, 0, 0x14000
	v_add_u32_e32 v142, s55, v188
	v_add_u32_e32 v171, s24, v188
	ds_read_b128 v[122:125], v142
	ds_read_b128 v[134:137], v142 offset:1024
	ds_read_b128 v[138:141], v142 offset:2048
	ds_read_b128 v[142:145], v142 offset:3072
	ds_read_b128 v[146:149], v171
	ds_read_b128 v[150:153], v171 offset:1024
	ds_read_b128 v[154:157], v171 offset:2048
	ds_read_b128 v[172:175], v171 offset:3072
	v_lshl_add_u64 v[184:185], s[50:51], 0, v[166:167]
	s_add_i32 m0, s57, 0xc000
	ds_read_b128 v[176:179], v190
	ds_read_b128 v[180:183], v190 offset:1024
	ds_read_b128 v[192:195], v190 offset:2048
	ds_read_b128 v[196:199], v190 offset:3072
	ds_read_b128 v[200:203], v190 offset:4096
	ds_read_b128 v[204:207], v190 offset:5120
	ds_read_b128 v[208:211], v190 offset:6144
	ds_read_b128 v[212:215], v190 offset:7168
	global_load_lds_dwordx4 v[184:185], off
	v_lshl_add_u64 v[184:185], s[50:51], 0, v[168:169]
	s_add_i32 m0, s57, 0xe000
	s_nop 0
	global_load_lds_dwordx4 v[184:185], off
	s_waitcnt vmcnt(8)
	s_waitcnt lgkmcnt(0)
	s_barrier
	s_setprio 1
	v_mfma_f32_16x16x32_bf16 v[130:133], v[122:125], v[176:179], v[130:133]
	v_mfma_f32_16x16x32_bf16 v[126:129], v[138:141], v[176:179], v[126:129]
	v_mfma_f32_16x16x32_bf16 v[110:113], v[122:125], v[192:195], v[110:113]
	v_mfma_f32_16x16x32_bf16 v[106:109], v[138:141], v[192:195], v[106:109]
	v_mfma_f32_16x16x32_bf16 v[94:97], v[122:125], v[200:203], v[94:97]
	v_mfma_f32_16x16x32_bf16 v[90:93], v[138:141], v[200:203], v[90:93]
	v_mfma_f32_16x16x32_bf16 v[78:81], v[122:125], v[208:211], v[78:81]
	v_mfma_f32_16x16x32_bf16 v[74:77], v[138:141], v[208:211], v[74:77]
	v_mfma_f32_16x16x32_bf16 v[130:133], v[134:137], v[180:183], v[130:133]
	v_mfma_f32_16x16x32_bf16 v[126:129], v[142:145], v[180:183], v[126:129]
	v_mfma_f32_16x16x32_bf16 v[110:113], v[134:137], v[196:199], v[110:113]
	v_mfma_f32_16x16x32_bf16 v[106:109], v[142:145], v[196:199], v[106:109]
	v_mfma_f32_16x16x32_bf16 v[94:97], v[134:137], v[204:207], v[94:97]
	v_mfma_f32_16x16x32_bf16 v[90:93], v[142:145], v[204:207], v[90:93]
	v_mfma_f32_16x16x32_bf16 v[78:81], v[134:137], v[212:215], v[78:81]
	v_mfma_f32_16x16x32_bf16 v[74:77], v[142:145], v[212:215], v[74:77]
	v_mfma_f32_16x16x32_bf16 v[118:121], v[146:149], v[176:179], v[118:121]
	v_mfma_f32_16x16x32_bf16 v[114:117], v[154:157], v[176:179], v[114:117]
	v_mfma_f32_16x16x32_bf16 v[102:105], v[146:149], v[192:195], v[102:105]
	v_mfma_f32_16x16x32_bf16 v[98:101], v[154:157], v[192:195], v[98:101]
	v_mfma_f32_16x16x32_bf16 v[86:89], v[146:149], v[200:203], v[86:89]
	v_mfma_f32_16x16x32_bf16 v[82:85], v[154:157], v[200:203], v[82:85]
	v_mfma_f32_16x16x32_bf16 v[70:73], v[146:149], v[208:211], v[70:73]
	v_mfma_f32_16x16x32_bf16 v[66:69], v[154:157], v[208:211], v[66:69]
	v_mfma_f32_16x16x32_bf16 v[118:121], v[150:153], v[180:183], v[118:121]
	v_mfma_f32_16x16x32_bf16 v[114:117], v[172:175], v[180:183], v[114:117]
	v_mfma_f32_16x16x32_bf16 v[102:105], v[150:153], v[196:199], v[102:105]
	v_mfma_f32_16x16x32_bf16 v[98:101], v[172:175], v[196:199], v[98:101]
	v_mfma_f32_16x16x32_bf16 v[86:89], v[150:153], v[204:207], v[86:89]
	v_mfma_f32_16x16x32_bf16 v[82:85], v[172:175], v[204:207], v[82:85]
	v_mfma_f32_16x16x32_bf16 v[70:73], v[150:153], v[212:215], v[70:73]
	v_mfma_f32_16x16x32_bf16 v[66:69], v[172:175], v[212:215], v[66:69]
	s_setprio 0
	s_barrier
	s_add_i32 s55, s55, s56
	v_lshl_add_u64 v[184:185], s[6:7], 0, v[162:163]
	s_mov_b32 m0, s55
	ds_read_b128 v[176:179], v190 offset:16384
	ds_read_b128 v[180:183], v190 offset:17408
	ds_read_b128 v[192:195], v190 offset:18432
	ds_read_b128 v[196:199], v190 offset:19456
	ds_read_b128 v[200:203], v190 offset:20480
	ds_read_b128 v[204:207], v190 offset:21504
	ds_read_b128 v[208:211], v190 offset:22528
	ds_read_b128 v[212:215], v190 offset:23552
	global_load_lds_dwordx4 v[184:185], off
	s_add_i32 m0, s55, 0x2000
	v_lshl_add_u64 v[216:217], s[6:7], 0, v[158:159]
	s_add_u32 s6, s6, s8
	s_addc_u32 s7, s7, 0
	s_add_i32 s24, s24, s56
	global_load_lds_dwordx4 v[216:217], off
	v_lshl_add_u64 v[218:219], s[6:7], 0, v[162:163]
	s_mov_b32 m0, s24
	v_lshl_add_u64 v[220:221], s[6:7], 0, v[158:159]
	global_load_lds_dwordx4 v[218:219], off
	s_add_i32 m0, s24, 0x2000
	v_lshl_add_u64 v[222:223], s[52:53], 0, v[164:165]
	global_load_lds_dwordx4 v[220:221], off
	s_mov_b32 m0, s57
	v_lshl_add_u64 v[224:225], s[52:53], 0, v[160:161]
	global_load_lds_dwordx4 v[222:223], off
	s_mov_b32 m0, s58
	s_nop 0
	global_load_lds_dwordx4 v[224:225], off
	s_waitcnt vmcnt(8)
	s_waitcnt lgkmcnt(0)
	s_barrier
	s_setprio 1
	v_mfma_f32_16x16x32_bf16 v[62:65], v[122:125], v[176:179], v[62:65]
	v_mfma_f32_16x16x32_bf16 v[58:61], v[138:141], v[176:179], v[58:61]
	v_mfma_f32_16x16x32_bf16 v[46:49], v[122:125], v[192:195], v[46:49]
	v_mfma_f32_16x16x32_bf16 v[42:45], v[138:141], v[192:195], v[42:45]
	v_mfma_f32_16x16x32_bf16 v[30:33], v[122:125], v[200:203], v[30:33]
	v_mfma_f32_16x16x32_bf16 v[26:29], v[138:141], v[200:203], v[26:29]
	v_mfma_f32_16x16x32_bf16 v[14:17], v[122:125], v[208:211], v[14:17]
	v_mfma_f32_16x16x32_bf16 v[10:13], v[138:141], v[208:211], v[10:13]
	v_mfma_f32_16x16x32_bf16 v[62:65], v[134:137], v[180:183], v[62:65]
	v_mfma_f32_16x16x32_bf16 v[58:61], v[142:145], v[180:183], v[58:61]
	v_mfma_f32_16x16x32_bf16 v[46:49], v[134:137], v[196:199], v[46:49]
	v_mfma_f32_16x16x32_bf16 v[42:45], v[142:145], v[196:199], v[42:45]
	v_mfma_f32_16x16x32_bf16 v[30:33], v[134:137], v[204:207], v[30:33]
	v_mfma_f32_16x16x32_bf16 v[26:29], v[142:145], v[204:207], v[26:29]
	v_mfma_f32_16x16x32_bf16 v[14:17], v[134:137], v[212:215], v[14:17]
	v_mfma_f32_16x16x32_bf16 v[10:13], v[142:145], v[212:215], v[10:13]
	v_mfma_f32_16x16x32_bf16 v[54:57], v[146:149], v[176:179], v[54:57]
	v_mfma_f32_16x16x32_bf16 v[50:53], v[154:157], v[176:179], v[50:53]
	v_mfma_f32_16x16x32_bf16 v[38:41], v[146:149], v[192:195], v[38:41]
	v_mfma_f32_16x16x32_bf16 v[34:37], v[154:157], v[192:195], v[34:37]
	v_mfma_f32_16x16x32_bf16 v[22:25], v[146:149], v[200:203], v[22:25]
	v_mfma_f32_16x16x32_bf16 v[18:21], v[154:157], v[200:203], v[18:21]
	v_mfma_f32_16x16x32_bf16 v[6:9], v[146:149], v[208:211], v[6:9]
	v_mfma_f32_16x16x32_bf16 v[2:5], v[154:157], v[208:211], v[2:5]
	v_mfma_f32_16x16x32_bf16 v[54:57], v[150:153], v[180:183], v[54:57]
	v_mfma_f32_16x16x32_bf16 v[50:53], v[172:175], v[180:183], v[50:53]
	v_mfma_f32_16x16x32_bf16 v[38:41], v[150:153], v[196:199], v[38:41]
	v_mfma_f32_16x16x32_bf16 v[34:37], v[172:175], v[196:199], v[34:37]
	v_mfma_f32_16x16x32_bf16 v[22:25], v[150:153], v[204:207], v[22:25]
	v_mfma_f32_16x16x32_bf16 v[18:21], v[172:175], v[204:207], v[18:21]
	v_mfma_f32_16x16x32_bf16 v[6:9], v[150:153], v[212:215], v[6:9]
	v_mfma_f32_16x16x32_bf16 v[2:5], v[172:175], v[212:215], v[2:5]
	s_setprio 0
	s_barrier
	s_add_i32 s24, 0, 0x18000
	s_add_i32 s55, 0, 0x1c000
	v_add_u32_e32 v142, s24, v188
	v_add_u32_e32 v171, s55, v188
	ds_read_b128 v[122:125], v142
	ds_read_b128 v[134:137], v142 offset:1024
	ds_read_b128 v[138:141], v142 offset:2048
	ds_read_b128 v[142:145], v142 offset:3072
	ds_read_b128 v[146:149], v171
	ds_read_b128 v[150:153], v171 offset:1024
	ds_read_b128 v[154:157], v171 offset:2048
	ds_read_b128 v[172:175], v171 offset:3072
	s_add_u32 s6, s52, s8
	s_addc_u32 s7, s53, 0
	s_mov_b32 m0, s59
	v_lshl_add_u64 v[226:227], s[6:7], 0, v[164:165]
	ds_read_b128 v[176:179], v190 offset:32768
	ds_read_b128 v[180:183], v190 offset:33792
	ds_read_b128 v[192:195], v190 offset:34816
	ds_read_b128 v[196:199], v190 offset:35840
	ds_read_b128 v[200:203], v190 offset:36864
	ds_read_b128 v[204:207], v190 offset:37888
	ds_read_b128 v[208:211], v190 offset:38912
	ds_read_b128 v[212:215], v190 offset:39936
	global_load_lds_dwordx4 v[226:227], off
	v_lshl_add_u64 v[226:227], s[6:7], 0, v[160:161]
	s_mov_b32 m0, s60
	s_nop 0
	global_load_lds_dwordx4 v[226:227], off
	s_waitcnt vmcnt(8)
	s_waitcnt lgkmcnt(0)
	s_barrier
	s_setprio 1
	v_mfma_f32_16x16x32_bf16 v[130:133], v[122:125], v[176:179], v[130:133]
	v_mfma_f32_16x16x32_bf16 v[126:129], v[138:141], v[176:179], v[126:129]
	v_mfma_f32_16x16x32_bf16 v[110:113], v[122:125], v[192:195], v[110:113]
	v_mfma_f32_16x16x32_bf16 v[106:109], v[138:141], v[192:195], v[106:109]
	v_mfma_f32_16x16x32_bf16 v[94:97], v[122:125], v[200:203], v[94:97]
	v_mfma_f32_16x16x32_bf16 v[90:93], v[138:141], v[200:203], v[90:93]
	v_mfma_f32_16x16x32_bf16 v[78:81], v[122:125], v[208:211], v[78:81]
	v_mfma_f32_16x16x32_bf16 v[74:77], v[138:141], v[208:211], v[74:77]
	v_mfma_f32_16x16x32_bf16 v[130:133], v[134:137], v[180:183], v[130:133]
	v_mfma_f32_16x16x32_bf16 v[126:129], v[142:145], v[180:183], v[126:129]
	v_mfma_f32_16x16x32_bf16 v[110:113], v[134:137], v[196:199], v[110:113]
	v_mfma_f32_16x16x32_bf16 v[106:109], v[142:145], v[196:199], v[106:109]
	v_mfma_f32_16x16x32_bf16 v[94:97], v[134:137], v[204:207], v[94:97]
	v_mfma_f32_16x16x32_bf16 v[90:93], v[142:145], v[204:207], v[90:93]
	v_mfma_f32_16x16x32_bf16 v[78:81], v[134:137], v[212:215], v[78:81]
	v_mfma_f32_16x16x32_bf16 v[74:77], v[142:145], v[212:215], v[74:77]
	v_mfma_f32_16x16x32_bf16 v[118:121], v[146:149], v[176:179], v[118:121]
	v_mfma_f32_16x16x32_bf16 v[114:117], v[154:157], v[176:179], v[114:117]
	v_mfma_f32_16x16x32_bf16 v[102:105], v[146:149], v[192:195], v[102:105]
	v_mfma_f32_16x16x32_bf16 v[98:101], v[154:157], v[192:195], v[98:101]
	v_mfma_f32_16x16x32_bf16 v[86:89], v[146:149], v[200:203], v[86:89]
	v_mfma_f32_16x16x32_bf16 v[82:85], v[154:157], v[200:203], v[82:85]
	v_mfma_f32_16x16x32_bf16 v[70:73], v[146:149], v[208:211], v[70:73]
	v_mfma_f32_16x16x32_bf16 v[66:69], v[154:157], v[208:211], v[66:69]
	v_mfma_f32_16x16x32_bf16 v[118:121], v[150:153], v[180:183], v[118:121]
	v_mfma_f32_16x16x32_bf16 v[114:117], v[172:175], v[180:183], v[114:117]
	v_mfma_f32_16x16x32_bf16 v[102:105], v[150:153], v[196:199], v[102:105]
	v_mfma_f32_16x16x32_bf16 v[98:101], v[172:175], v[196:199], v[98:101]
	v_mfma_f32_16x16x32_bf16 v[86:89], v[150:153], v[204:207], v[86:89]
	v_mfma_f32_16x16x32_bf16 v[82:85], v[172:175], v[204:207], v[82:85]
	v_mfma_f32_16x16x32_bf16 v[70:73], v[150:153], v[212:215], v[70:73]
	v_mfma_f32_16x16x32_bf16 v[66:69], v[172:175], v[212:215], v[66:69]
	s_setprio 0
	s_barrier
	s_add_i32 s6, s24, s56
	v_lshl_add_u64 v[184:185], v[184:185], 0, s[84:85]
	s_mov_b32 m0, s6
	ds_read_b128 v[176:179], v190 offset:49152
	ds_read_b128 v[180:183], v190 offset:50176
	ds_read_b128 v[192:195], v190 offset:51200
	ds_read_b128 v[196:199], v190 offset:52224
	ds_read_b128 v[200:203], v190 offset:53248
	ds_read_b128 v[204:207], v190 offset:54272
	ds_read_b128 v[208:211], v190 offset:55296
	ds_read_b128 v[212:215], v190 offset:56320
	global_load_lds_dwordx4 v[184:185], off
	v_lshl_add_u64 v[184:185], v[216:217], 0, s[84:85]
	s_add_i32 m0, s6, 0x2000
	s_add_i32 s6, s55, s56
	global_load_lds_dwordx4 v[184:185], off
	v_lshl_add_u64 v[184:185], v[218:219], 0, s[84:85]
	s_mov_b32 m0, s6
	s_nop 0
	global_load_lds_dwordx4 v[184:185], off
	v_lshl_add_u64 v[184:185], v[220:221], 0, s[84:85]
	s_add_i32 m0, s6, 0x2000
	s_nop 0
	global_load_lds_dwordx4 v[184:185], off
	v_lshl_add_u64 v[184:185], v[222:223], 0, s[84:85]
	s_mov_b32 m0, s65
	s_nop 0
	global_load_lds_dwordx4 v[184:185], off
	v_lshl_add_u64 v[184:185], v[224:225], 0, s[84:85]
	s_mov_b32 m0, s66
	s_nop 0
	global_load_lds_dwordx4 v[184:185], off
	s_waitcnt vmcnt(8)
	s_waitcnt lgkmcnt(0)
	s_barrier
	s_setprio 1
	v_mfma_f32_16x16x32_bf16 v[62:65], v[122:125], v[176:179], v[62:65]
	v_mfma_f32_16x16x32_bf16 v[58:61], v[138:141], v[176:179], v[58:61]
	v_mfma_f32_16x16x32_bf16 v[46:49], v[122:125], v[192:195], v[46:49]
	v_mfma_f32_16x16x32_bf16 v[42:45], v[138:141], v[192:195], v[42:45]
	v_mfma_f32_16x16x32_bf16 v[30:33], v[122:125], v[200:203], v[30:33]
	v_mfma_f32_16x16x32_bf16 v[26:29], v[138:141], v[200:203], v[26:29]
	v_mfma_f32_16x16x32_bf16 v[14:17], v[122:125], v[208:211], v[14:17]
	v_mfma_f32_16x16x32_bf16 v[10:13], v[138:141], v[208:211], v[10:13]
	v_mfma_f32_16x16x32_bf16 v[62:65], v[134:137], v[180:183], v[62:65]
	v_mfma_f32_16x16x32_bf16 v[58:61], v[142:145], v[180:183], v[58:61]
	v_mfma_f32_16x16x32_bf16 v[46:49], v[134:137], v[196:199], v[46:49]
	v_mfma_f32_16x16x32_bf16 v[42:45], v[142:145], v[196:199], v[42:45]
	v_mfma_f32_16x16x32_bf16 v[30:33], v[134:137], v[204:207], v[30:33]
	v_mfma_f32_16x16x32_bf16 v[26:29], v[142:145], v[204:207], v[26:29]
	v_mfma_f32_16x16x32_bf16 v[14:17], v[134:137], v[212:215], v[14:17]
	v_mfma_f32_16x16x32_bf16 v[10:13], v[142:145], v[212:215], v[10:13]
	v_mfma_f32_16x16x32_bf16 v[54:57], v[146:149], v[176:179], v[54:57]
	v_mfma_f32_16x16x32_bf16 v[50:53], v[154:157], v[176:179], v[50:53]
	v_mfma_f32_16x16x32_bf16 v[38:41], v[146:149], v[192:195], v[38:41]
	v_mfma_f32_16x16x32_bf16 v[34:37], v[154:157], v[192:195], v[34:37]
	v_mfma_f32_16x16x32_bf16 v[22:25], v[146:149], v[200:203], v[22:25]
	v_mfma_f32_16x16x32_bf16 v[18:21], v[154:157], v[200:203], v[18:21]
	v_mfma_f32_16x16x32_bf16 v[6:9], v[146:149], v[208:211], v[6:9]
	v_mfma_f32_16x16x32_bf16 v[2:5], v[154:157], v[208:211], v[2:5]
	v_mfma_f32_16x16x32_bf16 v[54:57], v[150:153], v[180:183], v[54:57]
	v_mfma_f32_16x16x32_bf16 v[50:53], v[172:175], v[180:183], v[50:53]
	v_mfma_f32_16x16x32_bf16 v[38:41], v[150:153], v[196:199], v[38:41]
	v_mfma_f32_16x16x32_bf16 v[34:37], v[172:175], v[196:199], v[34:37]
	v_mfma_f32_16x16x32_bf16 v[22:25], v[150:153], v[204:207], v[22:25]
	v_mfma_f32_16x16x32_bf16 v[18:21], v[172:175], v[204:207], v[18:21]
	v_mfma_f32_16x16x32_bf16 v[6:9], v[150:153], v[212:215], v[6:9]
	v_mfma_f32_16x16x32_bf16 v[2:5], v[172:175], v[212:215], v[2:5]
	s_setprio 0
	s_barrier
	s_add_u32 s50, s50, 0x100
	s_addc_u32 s51, s51, 0
	s_add_u32 s37, s37, 0x100
	s_addc_u32 s54, s54, 0
	s_cmp_ge_u32 s25, s62
	s_mov_b32 s24, s25
	s_cbranch_scc0 .LBB0_763
	s_and_b64 vcc, exec, s[44:45]
	s_cbranch_vccz .LBB0_766
	s_barrier
